# speedup vs baseline: 1.0023x; 1.0023x over previous
; __device__ __forceinline__ float bf2f(u16 h) { return __uint_as_float(((unsigned)h) << 16); }
; __device__ __forceinline__ float siluf_(float v) { return v * __builtin_amdgcn_rcpf(1.f + __expf(-v)); }
; template <int DUMMY>
; __device__ void ssd_item(const Params& p, int item) {
;     ...
;     {
;       float dec = __expf(cs[63]);
; #pragma unroll
;       for (int j = 0; j < 2; ++j) {
;         accS[j][0] *= dec; accS[j][1] *= dec; accS[j][2] *= dec; accS[j][3] *= dec;
;       }
; #pragma unroll
;       for (int ks = 0; ks < 2; ++ks) {
;         bf16x8 a = *(const bf16x8*)(xwT + (pf * 16 + fr) * 72 + ks * 32 + g4 * 8);
; #pragma unroll
;         for (int j = 0; j < 2; ++j) {
;           bf16x8 bb = *(const bf16x8*)(BTs + ((nf0 + j) * 16 + fr) * 72 + ks * 32 + g4 * 8);
;           accS[j] = __builtin_amdgcn_mfma_f32_16x16x32_bf16(a, bb, accS[j], 0, 0, 0);
;         }
;       }
;     }
;     __builtin_amdgcn_s_setprio(0);
;     RAW_BARRIER();
;     __builtin_amdgcn_s_setprio(1);
;     {
;       f32x4 yd = {0.f, 0.f, 0.f, 0.f}, yo = {0.f, 0.f, 0.f, 0.f};
; #pragma unroll
;       for (int ks = 0; ks < 2; ++ks) {
;         bf16x8 a = *(const bf16x8*)(Gs + (lf * 16 + fr) * 72 + ks * 32 + g4 * 8);
;         bf16x8 bb = *(const bf16x8*)(xdT + (pf * 16 + fr) * 72 + ks * 32 + g4 * 8);
;         yd = __builtin_amdgcn_mfma_f32_16x16x32_bf16(a, bb, yd, 0, 0, 0);
;       }
; #pragma unroll
;       for (int ks = 0; ks < 4; ++ks) {
;         bf16x8 a = *(const bf16x8*)(Cs + (lf * 16 + fr) * 136 + ks * 32 + g4 * 8);
;         bf16x8 bb = *(const bf16x8*)(Sb + (pf * 16 + fr) * 136 + ks * 32 + g4 * 8);
;         yo = __builtin_amdgcn_mfma_f32_16x16x32_bf16(a, bb, yo, 0, 0, 0);
;       }
;       __builtin_amdgcn_s_setprio(0);
;       bf16x4 xs4 = *(const bf16x4*)(xT + (pf * 16 + fr) * 72 + lf * 16 + g4 * 4);
; #pragma unroll
;       for (int r = 0; r < 4; ++r) {
;         int l_ = lf * 16 + g4 * 4 + r;
;         float y = yd[r] + __expf(cs[l_]) * yo[r] + Dh * bf2f((u16)xs4[r]);
;         y *= siluf_(bf2f(zcur[r]));
;         ytile[l_ * 36 + pf * 16 + fr] = f2bf(y);
;         float sq = row16_sum(y * y);
;         if (fr == 0) sqs[wid * 16 + g4 * 4 + r] = sq;
;       }
.LBB0_1024:
	s_or_b64 exec, exec, s[68:69]
	s_waitcnt lgkmcnt(8)
	ds_read_b32 v85, v105
	ds_write_b16 v131, v32
	ds_read_b128 v[32:35], v134 offset:57856
	s_waitcnt lgkmcnt(7)
	ds_read_b128 v[36:39], v136 offset:34816
	ds_read_b128 v[94:97], v138 offset:34816
	ds_read_b128 v[168:171], v134 offset:57920
	ds_read_b128 v[172:175], v136 offset:34880
	s_waitcnt lgkmcnt(6)
	v_mul_f32_e32 v85, 0x3fb8aa3b, v85
	v_exp_f32_e32 v156, v85
	s_nop 0
	v_pk_mul_f32 v[2:3], v[2:3], v[156:157] op_sel_hi:[1,0]
	v_pk_mul_f32 v[0:1], v[0:1], v[156:157] op_sel_hi:[1,0]
	v_pk_mul_f32 v[6:7], v[6:7], v[156:157] op_sel_hi:[1,0]
	v_pk_mul_f32 v[4:5], v[4:5], v[156:157] op_sel_hi:[1,0]
	s_waitcnt lgkmcnt(3)
	v_mfma_f32_16x16x32_bf16 v[0:3], v[32:35], v[36:39], v[0:3]
	ds_read_b128 v[36:39], v138 offset:34880
	s_waitcnt lgkmcnt(3)
	v_mfma_f32_16x16x32_bf16 v[32:35], v[32:35], v[94:97], v[4:7]
	s_waitcnt lgkmcnt(1)
	v_mfma_f32_16x16x32_bf16 v[4:7], v[168:171], v[172:175], v[0:3]
	s_waitcnt lgkmcnt(0)
	v_mfma_f32_16x16x32_bf16 v[0:3], v[168:171], v[36:39], v[32:35]
	s_setprio 0
	s_waitcnt lgkmcnt(0)
	s_barrier
	s_setprio 1
	s_nop 0
	ds_read_b128 v[32:35], v152
	v_add3_u32 v155, v161, v162, s93
	ds_read_b128 v[36:39], v132
	ds_read_b128 v[94:97], v155
	ds_read_b128 v[168:171], v152 offset:64
	ds_read_b128 v[172:175], v155 offset:64
	s_mov_b32 s3, 0x19c00
	v_add3_u32 v156, v160, v161, s3
	s_waitcnt lgkmcnt(2)
	v_mfma_f32_16x16x32_bf16 v[32:35], v[32:35], v[94:97], 0
	ds_read_b128 v[94:97], v156
	ds_read_b128 v[176:179], v132 offset:64
	ds_read_b128 v[180:183], v156 offset:64
	s_waitcnt lgkmcnt(2)
	v_mfma_f32_16x16x32_bf16 v[94:97], v[36:39], v[94:97], 0
	ds_read_b128 v[36:39], v152 offset:128
	ds_read_b128 v[184:187], v152 offset:192
	v_mfma_f32_16x16x32_bf16 v[32:35], v[168:171], v[172:175], v[32:35]
	ds_read_b128 v[168:171], v155 offset:128
	ds_read_b128 v[172:175], v155 offset:192
	s_waitcnt lgkmcnt(1)
	v_mfma_f32_16x16x32_bf16 v[32:35], v[36:39], v[168:171], v[32:35]
	s_waitcnt lgkmcnt(0)
	v_mfma_f32_16x16x32_bf16 v[36:39], v[184:187], v[172:175], v[32:35]
	v_mfma_f32_16x16x32_bf16 v[32:35], v[176:179], v[180:183], v[94:97]
	s_setprio 0
	v_lshl_add_u32 v85, v46, 1, v160
	s_mov_b32 s3, 0x1ae00
	s_waitcnt vmcnt(13)
	v_lshlrev_b32_e32 v95, 16, v100
	v_add3_u32 v157, v85, v164, s3
	ds_read_b32 v94, v84
	ds_read_b64 v[84:85], v157
	v_mul_f32_e32 v96, 0xbfb8aa3b, v95
	v_exp_f32_e32 v96, v96
	s_waitcnt lgkmcnt(1)
	v_mul_f32_e32 v94, 0x3fb8aa3b, v94
	v_exp_f32_e32 v94, v94
	v_add_f32_e32 v96, 1.0, v96
	v_rcp_f32_e32 v96, v96
	v_fma_f32 v32, v36, v94, v32
	s_waitcnt lgkmcnt(0)
	v_lshlrev_b32_e32 v36, 16, v84
	v_fmac_f32_e32 v32, v43, v36
	v_mul_f32_e32 v36, v96, v95
	v_mul_f32_e32 v32, v36, v32
	v_cvt_pk_bf16_f32 v36, v32, s0
	ds_write_b16 v123, v36
	v_mul_f32_e32 v36, v32, v32
	s_nop 1
	v_mov_b32_dpp v36, v36 quad_perm:[1,0,3,2] row_mask:0xf bank_mask:0xf bound_ctrl:1
	v_fmac_f32_e32 v36, v32, v32
	s_nop 1
	v_add_f32_dpp v32, v36, v36 quad_perm:[2,3,0,1] row_mask:0xf bank_mask:0xf bound_ctrl:1
	s_nop 1
	v_add_f32_dpp v32, v32, v32 row_half_mirror row_mask:0xf bank_mask:0xf bound_ctrl:1
	s_nop 1
	v_mov_b32_dpp v36, v32 row_mirror row_mask:0xf bank_mask:0xf bound_ctrl:1
	s_and_saveexec_b64 s[68:69], s[0:1]
	v_add_f32_e32 v32, v32, v36
	ds_write_b32 v122, v32
	s_or_b64 exec, exec, s[68:69]
	s_waitcnt vmcnt(12)
	v_lshlrev_b32_e32 v94, 16, v99
	ds_read_b32 v32, v42
	v_mul_f32_e32 v36, 0xbfb8aa3b, v94
	v_exp_f32_e32 v36, v36
	v_and_b32_e32 v95, 0xffff0000, v84
	s_waitcnt lgkmcnt(0)
	v_mul_f32_e32 v32, 0x3fb8aa3b, v32
	v_add_f32_e32 v36, 1.0, v36
	v_exp_f32_e32 v32, v32
	v_rcp_f32_e32 v42, v36
	v_fma_f32 v36, v37, v32, v33
	v_pk_mul_f32 v[32:33], v[42:43], v[94:95]
	s_nop 0
	v_add_f32_e32 v33, v33, v36
	v_mul_f32_e32 v32, v32, v33
	v_cvt_pk_bf16_f32 v33, v32, s0
	v_mul_f32_e32 v36, v32, v32
	ds_write_b16 v123, v33 offset:72
	s_nop 0
	v_mov_b32_dpp v33, v36 quad_perm:[1,0,3,2] row_mask:0xf bank_mask:0xf bound_ctrl:1
	v_fmac_f32_e32 v33, v32, v32
	s_nop 1
	v_add_f32_dpp v32, v33, v33 quad_perm:[2,3,0,1] row_mask:0xf bank_mask:0xf bound_ctrl:1
	s_nop 1
	v_add_f32_dpp v32, v32, v32 row_half_mirror row_mask:0xf bank_mask:0xf bound_ctrl:1
	s_nop 1
	v_mov_b32_dpp v33, v32 row_mirror row_mask:0xf bank_mask:0xf bound_ctrl:1
	s_and_saveexec_b64 s[68:69], s[0:1]
	v_add_f32_e32 v32, v32, v33
	ds_write_b32 v122, v32 offset:4
	s_or_b64 exec, exec, s[68:69]
	ds_read_b32 v33, v93
	s_waitcnt vmcnt(11)
	v_lshlrev_b32_e32 v32, 16, v61
	v_mul_f32_e32 v36, 0xbfb8aa3b, v32
	v_exp_f32_e32 v36, v36
	s_waitcnt lgkmcnt(0)
	v_mul_f32_e32 v33, 0x3fb8aa3b, v33
	v_exp_f32_e32 v37, v33
	v_add_f32_e32 v33, 1.0, v36
	v_rcp_f32_e32 v42, v33
	v_lshlrev_b32_e32 v33, 16, v85
	v_fma_f32 v34, v38, v37, v34
	v_pk_mul_f32 v[32:33], v[42:43], v[32:33]
	s_nop 0
	v_add_f32_e32 v33, v33, v34
	v_mul_f32_e32 v32, v32, v33
	v_cvt_pk_bf16_f32 v33, v32, s0
	v_mul_f32_e32 v34, v32, v32
	ds_write_b16 v123, v33 offset:144
	s_nop 0
	v_mov_b32_dpp v33, v34 quad_perm:[1,0,3,2] row_mask:0xf bank_mask:0xf bound_ctrl:1
	v_fmac_f32_e32 v33, v32, v32
	s_nop 1
	v_add_f32_dpp v32, v33, v33 quad_perm:[2,3,0,1] row_mask:0xf bank_mask:0xf bound_ctrl:1
	s_nop 1
	v_add_f32_dpp v32, v32, v32 row_half_mirror row_mask:0xf bank_mask:0xf bound_ctrl:1
	s_nop 1
	v_mov_b32_dpp v33, v32 row_mirror row_mask:0xf bank_mask:0xf bound_ctrl:1
	s_and_saveexec_b64 s[68:69], s[0:1]
	v_add_f32_e32 v32, v32, v33
	ds_write_b32 v122, v32 offset:8
	s_or_b64 exec, exec, s[68:69]
	ds_read_b32 v33, v45
	s_waitcnt vmcnt(10)
	v_lshlrev_b32_e32 v32, 16, v57
	v_mul_f32_e32 v34, 0xbfb8aa3b, v32
	v_exp_f32_e32 v34, v34
	s_waitcnt lgkmcnt(0)
; __device__ __forceinline__ float bf2f(u16 h) { return __uint_as_float(((unsigned)h) << 16); }
; template <int DUMMY>
; __device__ void ssd_item(const Params& p, int item) {
;     ...
;   size_t zbase = (tb + lf * 16 + g4 * 4) * 4096 + h * 64 + ph * 32 + pf * 16 + fr;
; #pragma unroll
;   for (int r = 0; r < 4; ++r) { znext[r] = zy[zbase + (size_t)r * 4096]; zcur[r] = 0; }
;   __syncthreads();
;   int cur3 = 0;
;   for (int c = 0; c < 128; ++c) {
;     const int par = c & 1;
;     const int nxt3 = cur3 == 2 ? 0 : cur3 + 1;
;     u16* const Cs = par ? Cs1 : Cs0;
;     u16* const xdT = par ? xdT1 : xdT0;
;     u16* const xT = par ? xT1 : xT0;
;     u16* const Sb = par ? Sb1 : Sb0;
;     const float* cs = csb + cur3 * 64;
;     const float* dv = dtv + cur3 * 64;
;     {
; #pragma unroll
;       for (int i = 0; i < 2; ++i) {
;         int idx = tid + i * NT;
;         *(i32x4*)(Bs + (idx >> 4) * 136 + (idx & 15) * 8) = rBs[i];
;         *(i32x4*)(Cs + (idx >> 4) * 136 + (idx & 15) * 8) = rCs[i];
;         int c8 = idx >> 6, ll = idx & 63;
; #pragma unroll
;         for (int e = 0; e < 4; ++e) {
;           unsigned u = (unsigned)rBT[i][e];
;           BTs[(c8 * 8 + 2 * e) * 72 + ll] = (u16)(u & 0xffffu);
;           BTs[(c8 * 8 + 2 * e + 1) * 72 + ll] = (u16)(u >> 16);
;         }
;       }
;       {
;         float w0 = cwX[0 * 32 + chg], w1 = cwX[1 * 32 + chg], w2 = cwX[2 * 32 + chg], w3 = cwX[3 * 32 + chg], bx = cwX[4 * 32 + chg];
;         float raw[7];
; #pragma unroll
;         for (int i = 0; i < 7; ++i) raw[i] = bf2f(rX[i]);
;         const float cs63 = cs[63];
;         float4 dt4 = *(const float4*)(dv + l0), cs4 = *(const float4*)(cs + l0);
;         float dts[4] = {dt4.x, dt4.y, dt4.z, dt4.w}, css[4] = {cs4.x, cs4.y, cs4.z, cs4.w};
	v_mul_f32_e32 v33, 0x3fb8aa3b, v33
	v_exp_f32_e32 v36, v33
	v_add_f32_e32 v33, 1.0, v34
	v_rcp_f32_e32 v42, v33
	v_and_b32_e32 v33, 0xffff0000, v85
	v_fmac_f32_e32 v35, v39, v36
	v_pk_mul_f32 v[32:33], v[42:43], v[32:33]
	s_nop 0
	v_add_f32_e32 v33, v33, v35
	v_mul_f32_e32 v32, v32, v33
	v_cvt_pk_bf16_f32 v33, v32, s0
	v_mul_f32_e32 v34, v32, v32
	ds_write_b16 v123, v33 offset:216
	s_nop 0
	v_mov_b32_dpp v33, v34 quad_perm:[1,0,3,2] row_mask:0xf bank_mask:0xf bound_ctrl:1
	v_fmac_f32_e32 v33, v32, v32
	s_nop 1
	v_add_f32_dpp v32, v33, v33 quad_perm:[2,3,0,1] row_mask:0xf bank_mask:0xf bound_ctrl:1
	s_nop 1
	v_add_f32_dpp v32, v32, v32 row_half_mirror row_mask:0xf bank_mask:0xf bound_ctrl:1
	s_nop 1
	v_mov_b32_dpp v33, v32 row_mirror row_mask:0xf bank_mask:0xf bound_ctrl:1
	s_and_saveexec_b64 s[68:69], s[0:1]
	v_add_f32_e32 v32, v32, v33
	ds_write_b32 v122, v32 offset:12
	s_or_b64 exec, exec, s[68:69]
	s_lshl_b32 s52, s83, 4
	s_and_b32 s52, s52, 0xe0
	s_lshl_b32 s53, s70, 4
	s_add_i32 s70, s52, s53
	s_and_b32 s58, s72, 1
	s_or_b32 s72, s70, s71
	s_lshl_b64 s[52:53], s[30:31], 26
	v_lshl_or_b32 v32, v58, 15, s52
	v_mov_b32_e32 v33, s53
	v_lshlrev_b64 v[34:35], 13, v[46:47]
	s_lshl_b32 s71, s72, 6
	v_lshl_add_u64 v[84:85], v[32:33], 0, v[34:35]
	s_and_b32 s73, s71, 0x1f80
	s_lshl_b32 s3, s58, 6
	v_or_b32_e32 v32, s73, v84
	v_lshrrev_b32_e32 v33, 1, v40
	v_or_b32_e32 v32, s3, v32
	v_and_b32_e32 v33, 32, v33
	v_lshlrev_b32_e32 v34, 1, v56
	s_lshl_b64 s[68:69], s[30:31], 25
	v_or3_b32 v84, v32, v33, v34
	v_lshlrev_b64 v[32:33], 12, v[80:81]
	s_lshl_b32 s70, s70, 4
	v_lshl_add_u64 v[32:33], s[68:69], 0, v[32:33]
	s_and_b32 s70, s70, 0x700
	v_lshlrev_b32_e32 v36, 4, v56
	v_or3_b32 v32, v32, s70, v36
	v_lshl_add_u64 v[80:81], s[40:41], 0, v[32:33]
	v_lshl_or_b32 v32, v98, 12, s68
	v_or_b32_e32 v32, s70, v32
	v_mov_b32_e32 v33, s69
	v_lshl_add_u64 v[34:35], v[64:65], 1, v[32:33]
	v_lshl_add_u64 v[32:33], v[62:63], 1, v[32:33]
	s_waitcnt vmcnt(4)
	v_perm_b32 v42, v92, v91, s94
	v_perm_b32 v100, v91, v90, s94
	v_perm_b32 v101, v90, v88, s94
	v_lshl_add_u64 v[90:91], s[56:57], 0, v[32:33]
	v_lshlrev_b64 v[32:33], 12, v[78:79]
	v_lshl_add_u64 v[32:33], s[68:69], 0, v[32:33]
	s_bfe_u32 s96, s72, 0x60001
	v_or3_b32 v32, v32, s70, v36
	s_lshl_b64 s[70:71], s[30:31], 21
	s_add_u32 s70, s70, 0x17110000
	v_lshl_add_u64 v[78:79], s[40:41], 0, v[32:33]
	s_addc_u32 s71, s71, 0
	v_lshlrev_b64 v[32:33], 8, v[40:41]
	v_lshl_add_u64 v[92:93], s[70:71], 0, v[32:33]
	s_lshl_b32 s70, s72, 1
	s_and_b32 s70, s70, 0xfc
	v_or_b32_e32 v92, s70, v92
	s_add_u32 s70, s64, 64
	s_addc_u32 s71, s65, 0
	s_lshl_b64 s[30:31], s[30:31], 22
	v_lshl_add_u64 v[32:33], s[70:71], 0, v[48:49]
	s_add_u32 s30, s30, 0x4208000
	v_lshl_add_u64 v[32:33], v[32:33], 0, v[46:47]
	s_addc_u32 s31, s31, 0
	v_perm_b32 v173, v88, v89, s94
	v_lshl_add_u64 v[88:89], s[56:57], 0, v[34:35]
	v_lshlrev_b64 v[94:95], 9, v[32:33]
	v_lshl_or_b32 v32, v58, 11, s30
	v_mov_b32_e32 v33, s31
	v_lshlrev_b64 v[34:35], 9, v[46:47]
	s_lshl_b32 s30, s72, 2
	v_lshl_add_u64 v[96:97], v[32:33], 0, v[34:35]
	s_and_b32 s30, s30, 0x1f8
	v_ashrrev_i32_e32 v45, 31, v44
	v_or_b32_e32 v32, s30, v96
	s_add_u32 s30, s52, 0xb100000
	v_lshl_or_b32 v96, s58, 2, v32
	s_addc_u32 s31, s53, 0
	v_lshlrev_b64 v[32:33], 13, v[44:45]
	v_lshl_add_u64 v[98:99], s[30:31], 0, v[32:33]
	v_and_b32_e32 v33, 7, v40
	v_or_b32_e32 v32, s73, v98
	v_lshlrev_b32_e32 v33, 3, v33
	v_mov_b32_e32 v61, v41
	v_mov_b32_e32 v57, v41
	v_perm_b32 v171, v87, v86, s94
	v_add_u32_e32 v86, 0xc3, v50
	s_mov_b32 s97, 2
	v_or3_b32 v98, v32, s3, v33
	s_mov_b64 s[70:71], 0
	s_mov_b32 s76, 2
	v_readfirstlane_b32 s32, v214
	s_nop 3
	s_cmp_ge_u32 s32, 0x100
	s_cbranch_scc0 .Lssd_p2
	s_setprio 1
.Lssd_p2:
.LBB0_1033:
	s_bfe_i32 s3, s76, 0x10000
	s_and_b32 s3, s3, 0x15800
	v_lshl_or_b32 v32, v59, 1, s3
	s_lshl_b32 s31, s97, 8
	ds_write_b128 v116, v[20:23] offset:17408
	v_lshl_add_u32 v20, v146, 1, v32
	s_add_i32 s52, s31, 0x1e200
	ds_write_b128 v20, v[16:19]
	ds_write_b16 v52, v12 offset:34816
	ds_write_b16_d16_hi v52, v12 offset:34960
	ds_write_b16 v52, v13 offset:35104
	ds_write_b16_d16_hi v52, v13 offset:35248
	ds_write_b16 v52, v14 offset:35392
	ds_write_b16_d16_hi v52, v14 offset:35536
	ds_write_b16 v52, v15 offset:35680
	ds_write_b16_d16_hi v52, v15 offset:35824
	ds_write_b128 v117, v[24:27] offset:17408
	v_lshl_add_u32 v12, v147, 1, v32
	ds_write_b128 v12, v[28:31]
	ds_write_b16 v54, v8 offset:34816
	ds_write_b16_d16_hi v54, v8 offset:34960
	ds_write_b16 v54, v9 offset:35104
	ds_write_b16_d16_hi v54, v9 offset:35248
	ds_write_b16 v54, v10 offset:35392
	ds_write_b16_d16_hi v54, v10 offset:35536
	ds_write_b16 v54, v11 offset:35680
	ds_write_b16_d16_hi v54, v11 offset:35824
	v_mov_b32_e32 v8, s52
	ds_read2_b32 v[16:17], v115 offset1:32
	ds_read2_b32 v[18:19], v115 offset0:64 offset1:96
	ds_read_b32 v20, v115 offset:512
	ds_read_b32 v21, v8 offset:252
	v_and_b32_e32 v23, 0xffff0000, v173
	v_lshlrev_b32_e32 v22, 16, v173
	v_and_b32_e32 v13, 0xffff0000, v171
	v_lshlrev_b32_e32 v12, 16, v171
	v_add_u32_e32 v31, s31, v114
	v_lshlrev_b32_e32 v24, 16, v101
	s_waitcnt lgkmcnt(0)
; __device__ __forceinline__ float bf2f(u16 h) { return __uint_as_float(((unsigned)h) << 16); }
; __device__ __forceinline__ float siluf_(float v) { return v * __builtin_amdgcn_rcpf(1.f + __expf(-v)); }
; template <int DUMMY>
; __device__ void ssd_item(const Params& p, int item) {
;     ...
;       {
;         float w0 = cwX[0 * 32 + chg], w1 = cwX[1 * 32 + chg], w2 = cwX[2 * 32 + chg], w3 = cwX[3 * 32 + chg], bx = cwX[4 * 32 + chg];
;         float raw[7];
; #pragma unroll
;         for (int i = 0; i < 7; ++i) raw[i] = bf2f(rX[i]);
;         const float cs63 = cs[63];
;         float4 dt4 = *(const float4*)(dv + l0), cs4 = *(const float4*)(cs + l0);
;         float dts[4] = {dt4.x, dt4.y, dt4.z, dt4.w}, css[4] = {cs4.x, cs4.y, cs4.z, cs4.w};
;         float vx[4], vd[4], vw[4];
; #pragma unroll
;         for (int j = 0; j < 4; ++j) {
;           float s = bx + w0 * raw[j] + w1 * raw[j + 1] + w2 * raw[j + 2] + w3 * raw[j + 3];
;           vx[j] = siluf_(s);
;           vd[j] = vx[j] * dts[j];
;           vw[j] = vd[j] * __expf(cs63 - css[j]);
;         }
;         *(i32x2*)(xT + chg * 72 + l0) = i32x2{(int)pack2(vx[0], vx[1]), (int)pack2(vx[2], vx[3])};
;         *(i32x2*)(xdT + chg * 72 + l0) = i32x2{(int)pack2(vd[0], vd[1]), (int)pack2(vd[2], vd[3])};
;         *(i32x2*)(xwT + chg * 72 + l0) = i32x2{(int)pack2(vw[0], vw[1]), (int)pack2(vw[2], vw[3])};
;       }
;     }
; #pragma unroll
;     for (int j = 0; j < 2; ++j)
; #pragma unroll
;       for (int r = 0; r < 4; ++r) Sb[(pf * 16 + g4 * 4 + r) * 136 + (nf0 + j) * 16 + fr] = f2bf(accS[j][r]);
; #pragma unroll
;     for (int r = 0; r < 4; ++r) zcur[r] = znext[r];
;     if (c > 1) {
;       const size_t yi = (tb + (c - 2) * 64 + (tid >> 3)) * 4096 + h * 64 + ph * 32 + (tid & 7) * 4;
;       *(i32x2*)(zyo + (yi & omask)) = ypend;
;     }
;     if (c + 1 < 128) {
;       load_raw(c + 1);
;       const size_t zn = zbase + (size_t)64 * 4096;
; #pragma unroll
;       for (int r = 0; r < 4; ++r) znext[r] = zy[zn + (size_t)r * 4096];
;       if (wid == 0) {
;         float dt_use = dt_n;
;         if (c + 2 < 128) dt_n = dtb[(tb + (c + 2) * 64 + lane) * 64 + h];
;         write_cs(dt_use, nxt3);
	v_pk_fma_f32 v[14:15], v[16:17], v[12:13], v[20:21] op_sel_hi:[0,1,0]
	v_mov_b32_e32 v30, v17
	v_pk_mov_b32 v[12:13], v[12:13], v[22:23] op_sel:[1,0]
	v_lshlrev_b32_e32 v26, 16, v100
	v_pk_fma_f32 v[12:13], v[30:31], v[12:13], v[14:15] op_sel_hi:[0,1,1]
	v_mov_b32_e32 v14, v22
	v_mov_b32_e32 v15, v24
	v_pk_fma_f32 v[12:13], v[18:19], v[14:15], v[12:13] op_sel_hi:[0,1,1]
	v_mov_b32_e32 v32, v19
	v_mov_b32_e32 v14, v24
	v_mov_b32_e32 v15, v26
	v_pk_fma_f32 v[12:13], v[32:33], v[14:15], v[12:13] op_sel_hi:[0,1,1]
	v_and_b32_e32 v25, 0xffff0000, v101
	v_mul_f32_e32 v14, 0xbfb8aa3b, v12
	v_mul_f32_e32 v15, 0xbfb8aa3b, v13
	v_pk_fma_f32 v[16:17], v[16:17], v[22:23], v[20:21] op_sel_hi:[0,1,0]
	v_and_b32_e32 v27, 0xffff0000, v100
	v_exp_f32_e32 v14, v14
	v_exp_f32_e32 v15, v15
	v_pk_fma_f32 v[16:17], v[30:31], v[24:25], v[16:17] op_sel_hi:[0,1,1]
	v_and_b32_e32 v29, 0xffff0000, v42
	v_lshlrev_b32_e32 v28, 16, v42
	v_pk_fma_f32 v[16:17], v[18:19], v[26:27], v[16:17] op_sel_hi:[0,1,1]
	v_pk_fma_f32 v[16:17], v[32:33], v[28:29], v[16:17] op_sel_hi:[0,1,1]
	v_lshl_add_u32 v8, v50, 2, s52
	v_mul_f32_e32 v18, 0xbfb8aa3b, v16
	v_mul_f32_e32 v19, 0xbfb8aa3b, v17
	ds_read_b128 v[8:11], v8
	v_add_f32_e32 v14, 1.0, v14
	v_add_f32_e32 v15, 1.0, v15
	v_exp_f32_e32 v18, v18
	v_exp_f32_e32 v19, v19
	v_rcp_f32_e32 v14, v14
	v_rcp_f32_e32 v15, v15
	v_add_f32_e32 v18, 1.0, v18
	v_add_f32_e32 v19, 1.0, v19
	v_rcp_f32_e32 v18, v18
	v_pk_mul_f32 v[34:35], v[12:13], v[14:15]
	ds_read_b128 v[12:15], v31
	s_waitcnt lgkmcnt(1)
	v_sub_f32_e32 v8, v21, v8
	v_sub_f32_e32 v9, v21, v9
	v_sub_f32_e32 v10, v21, v10
	v_rcp_f32_e32 v19, v19
	v_sub_f32_e32 v11, v21, v11
	v_mul_f32_e32 v8, 0x3fb8aa3b, v8
	v_mul_f32_e32 v9, 0x3fb8aa3b, v9
	v_mul_f32_e32 v10, 0x3fb8aa3b, v10
	v_mul_f32_e32 v11, 0x3fb8aa3b, v11
	v_exp_f32_e32 v8, v8
	v_exp_f32_e32 v9, v9
	v_exp_f32_e32 v10, v10
	v_exp_f32_e32 v11, v11
	s_and_b32 s30, s76, 1
	s_cmp_eq_u32 s30, 0
	s_mov_b32 s30, 0xf400
	v_pk_mul_f32 v[16:17], v[16:17], v[18:19]
	s_cselect_b32 s77, s30, 0x1ae00
	s_waitcnt lgkmcnt(0)
	v_pk_mul_f32 v[12:13], v[12:13], v[34:35]
	v_pk_mul_f32 v[14:15], v[14:15], v[16:17]
	s_mov_b32 s30, 0xd000
	v_pk_mul_f32 v[8:9], v[8:9], v[12:13]
	v_pk_mul_f32 v[10:11], v[14:15], v[10:11]
	s_cselect_b32 s53, s30, 0x19c00
	v_cvt_pk_bf16_f32 v19, v16, v17
	v_lshlrev_b32_e32 v16, 1, v143
	s_cselect_b32 s78, 0x12a00, s93
	v_cvt_pk_bf16_f32 v18, v34, v35
	v_add3_u32 v17, s77, v16, v144
	v_cvt_pk_bf16_f32 v12, v12, v13
	v_cvt_pk_bf16_f32 v13, v14, v15
	v_add3_u32 v14, s53, v16, v144
	v_cvt_pk_bf16_f32 v8, v8, v9
	v_cvt_pk_bf16_f32 v9, v10, v11
	ds_write_b64 v17, v[18:19]
	ds_write_b64 v14, v[12:13]
	ds_write_b64 v113, v[8:9] offset:57856
	v_lshl_or_b32 v8, v56, 1, s78
	v_cvt_pk_bf16_f32 v9, v4, s0
	v_add3_u32 v10, v8, v55, v159
	ds_write_b16 v10, v9
	v_cvt_pk_bf16_f32 v9, v5, s0
	ds_write_b16 v10, v9 offset:272
	v_cvt_pk_bf16_f32 v9, v6, s0
	ds_write_b16 v10, v9 offset:544
	v_cvt_pk_bf16_f32 v9, v7, s0
	ds_write_b16 v10, v9 offset:816
	v_cvt_pk_bf16_f32 v9, v0, s0
	v_add3_u32 v8, v8, v153, v159
	ds_write_b16 v8, v9
	v_cvt_pk_bf16_f32 v9, v1, s0
	ds_write_b16 v8, v9 offset:272
	v_cvt_pk_bf16_f32 v9, v2, s0
	ds_write_b16 v8, v9 offset:544
	v_cvt_pk_bf16_f32 v9, v3, s0
	ds_write_b16 v8, v9 offset:816
	v_lshl_add_u64 v[8:9], s[42:43], 0, v[98:99]
	global_store_dwordx2 v[8:9], v[82:83], off
	v_lshl_add_u64 v[8:9], v[78:79], 0, s[70:71]
	s_mov_b32 s30, 0xc0000
	v_add_co_u32_e32 v8, vcc, s30, v8
	v_add_u32_e32 v40, -6, v86
	s_nop 0
	v_addc_co_u32_e32 v9, vcc, 0, v9, vcc
	global_load_dwordx4 v[20:23], v[8:9], off
	global_load_dwordx4 v[16:19], v[8:9], off offset:2048
	v_lshl_add_u64 v[8:9], v[90:91], 0, s[70:71]
	global_load_dwordx4 v[12:15], v[8:9], off
	v_lshl_add_u64 v[8:9], v[80:81], 0, s[70:71]
	v_add_co_u32_e32 v8, vcc, 0xc0000, v8
	v_mov_b32_e32 v172, 0
	s_nop 0
	v_addc_co_u32_e32 v9, vcc, 0, v9, vcc
	global_load_dwordx4 v[24:27], v[8:9], off
	global_load_dwordx4 v[28:31], v[8:9], off offset:2048
	v_lshl_add_u64 v[8:9], v[88:89], 0, s[70:71]
	global_load_dwordx4 v[8:11], v[8:9], off
	v_lshl_add_u64 v[32:33], s[64:65], 0, v[40:41]
	v_mad_u64_u32 v[34:35], s[72:73], v32, s86, v[66:67]
	v_mad_i32_i24 v35, v33, s86, v35
	global_load_ushort v171, v[34:35], off
	v_add_co_u32_e32 v34, vcc, 0x3000, v34
	s_nop 1
	v_addc_co_u32_e32 v35, vcc, 0, v35, vcc
	global_load_ushort v172, v[34:35], off
	v_add_co_u32_e32 v34, vcc, 0x3000, v34
	s_nop 1
	v_addc_co_u32_e32 v35, vcc, 0, v35, vcc
	global_load_ushort v174, v[34:35], off
	v_add_co_u32_e32 v34, vcc, 0x3000, v34
	s_nop 1
	v_addc_co_u32_e32 v35, vcc, 0, v35, vcc
	global_load_ushort v173, v[34:35], off
	v_add_co_u32_e32 v34, vcc, 0x3000, v34
	s_nop 1
	v_addc_co_u32_e32 v35, vcc, 0, v35, vcc
	global_load_ushort v175, v[34:35], off
	v_add_co_u32_e32 v34, vcc, 0x3000, v34
	s_nop 1
	v_addc_co_u32_e32 v35, vcc, 0, v35, vcc
	global_load_ushort v176, v[34:35], off
	v_add_co_u32_e32 v34, vcc, 0x3000, v34
	s_nop 1
	v_addc_co_u32_e32 v35, vcc, 0, v35, vcc
	global_load_ushort v40, v[34:35], off
	v_lshl_add_u64 v[32:33], s[42:43], 0, v[84:85]
	v_add_co_u32_e32 v34, vcc, 0xb280000, v32
	s_add_i32 s30, s97, 1
	s_nop 0
	v_addc_co_u32_e32 v35, vcc, 0, v33, vcc
	global_load_ushort v170, v[34:35], off
	v_add_co_u32_e32 v34, vcc, 0xb282000, v32
	s_cmp_lg_u32 s97, 2
	s_nop 0
	v_addc_co_u32_e32 v35, vcc, 0, v33, vcc
	global_load_ushort v169, v[34:35], off
	v_add_co_u32_e32 v34, vcc, 0xb284000, v32
	s_cselect_b32 s97, s30, 0
	s_nop 0
	v_addc_co_u32_e32 v35, vcc, 0, v33, vcc
	v_add_co_u32_e32 v32, vcc, 0xb286000, v32
	global_load_ushort v168, v[34:35], off
	s_nop 0
	v_addc_co_u32_e32 v33, vcc, 0, v33, vcc
	global_load_ushort v49, v[32:33], off
	s_and_saveexec_b64 s[30:31], s[4:5]
	s_cbranch_execz .LBB0_1049
	v_lshl_add_u64 v[32:33], s[42:43], 0, v[92:93]
	global_load_dword v255, v[32:33], off
	v_mul_f32_e64 v33, v118, -v120
	s_nop 1
	v_mov_b32_dpp v33, v33 row_shr:1 row_mask:0xf bank_mask:0xf bound_ctrl:1
	v_fma_f32 v33, v118, -v120, v33
	s_nop 1
	v_add_f32_dpp v33, v33, v33 row_shr:2 row_mask:0xf bank_mask:0xf bound_ctrl:1
	s_nop 1
	v_add_f32_dpp v33, v33, v33 row_shr:4 row_mask:0xf bank_mask:0xf bound_ctrl:1
	s_nop 1
	v_add_f32_dpp v33, v33, v33 row_shr:8 row_mask:0xf bank_mask:0xf bound_ctrl:1
	s_nop 0
	v_readlane_b32 s72, v33, 15
	v_readlane_b32 s73, v33, 31
	v_readlane_b32 vcc_lo, v33, 47
	v_mov_b32_e32 v34, s72
	v_mov_b32_e32 v35, s73
	v_cndmask_b32_e64 v34, v34, 0, s[26:27]
	v_cndmask_b32_e64 v35, 0, v35, s[24:25]
	v_add_f32_e32 v34, v34, v35
	v_mov_b32_e32 v35, vcc_lo
	v_cndmask_b32_e64 v35, 0, v35, s[22:23]
	v_add_f32_e32 v34, v35, v34
	v_add_f32_e32 v33, v33, v34
	v_lshl_or_b32 v34, s97, 8, v135
	v_add_u32_e32 v35, 0x1e200, v34
	ds_write_b32 v35, v33
	v_add_u32_e32 v33, 0x1e500, v34
	ds_write_b32 v33, v118

; template <int DUMMY>
; __device__ void ssd_item(const Params& p, int item) {
;     ...
;     __builtin_amdgcn_s_setprio(1);
;     {
;       const int sfb = (wid & 1) * 2;
;       f32x4 cb[2];
;       cb[0] = f32x4{0.f, 0.f, 0.f, 0.f};
;       cb[1] = f32x4{0.f, 0.f, 0.f, 0.f};
; #pragma unroll
;       for (int ks = 0; ks < 4; ++ks) {
;         bf16x8 a = *(const bf16x8*)(Cs + (lf * 16 + fr) * 136 + ks * 32 + g4 * 8);
; #pragma unroll
;         for (int j = 0; j < 2; ++j) {
;           bf16x8 bb = *(const bf16x8*)(Bs + ((sfb + j) * 16 + fr) * 136 + ks * 32 + g4 * 8);
;           cb[j] = __builtin_amdgcn_mfma_f32_16x16x32_bf16(a, bb, cb[j], 0, 0, 0);
;         }
;       }
; #pragma unroll
;       for (int j = 0; j < 2; ++j) {
;         int s_ = (sfb + j) * 16 + fr;
;         float cs_s = cs[s_];
; #pragma unroll
;         for (int r = 0; r < 4; ++r) {
;           int l_ = lf * 16 + g4 * 4 + r;
;           float gv = (s_ <= l_) ? cb[j][r] * __expf(cs[l_] - cs_s) : 0.f;
;           Gs[l_ * 72 + s_] = f2bf(gv);
;         }
;       }
;     }
;     {
;       float dec = __expf(cs[63]);
; #pragma unroll
;       for (int j = 0; j < 2; ++j) {
;         accS[j][0] *= dec; accS[j][1] *= dec; accS[j][2] *= dec; accS[j][3] *= dec;
;       }
; #pragma unroll
;       for (int ks = 0; ks < 2; ++ks) {
;         bf16x8 a = *(const bf16x8*)(xwT + (pf * 16 + fr) * 72 + ks * 32 + g4 * 8);
; #pragma unroll
;         for (int j = 0; j < 2; ++j) {
;           bf16x8 bb = *(const bf16x8*)(BTs + ((nf0 + j) * 16 + fr) * 72 + ks * 32 + g4 * 8);
;           accS[j] = __builtin_amdgcn_mfma_f32_16x16x32_bf16(a, bb, accS[j], 0, 0, 0);
;         }
;       }
;     }
;     __builtin_amdgcn_s_setprio(0);
.LBB0_1051:
	s_or_b64 exec, exec, s[30:31]
	v_add3_u32 v42, s3, v158, v161
	ds_read_b128 v[32:35], v42
	ds_read_b128 v[36:39], v154 offset:17408
	ds_read_b128 v[178:181], v154 offset:21760
	ds_read_b128 v[182:185], v42 offset:64
	ds_read_b128 v[186:189], v154 offset:17472
	ds_read_b128 v[220:223], v154 offset:21824
	ds_read_b128 v[224:227], v42 offset:128
	ds_read_b128 v[228:231], v154 offset:17536
	v_lshl_add_u32 v100, v121, 2, s52
	v_mov_b32_e32 v177, 0
	v_lshl_add_u32 v87, v119, 2, s52
	s_waitcnt lgkmcnt(6)
	v_mfma_f32_16x16x32_bf16 v[36:39], v[32:35], v[36:39], 0
	s_waitcnt lgkmcnt(5)
	v_mfma_f32_16x16x32_bf16 v[32:35], v[32:35], v[178:181], 0
	ds_read_b128 v[232:235], v154 offset:21888
	ds_read_b128 v[236:239], v42 offset:192
	ds_read_b128 v[240:243], v154 offset:17600
	ds_read_b128 v[244:247], v154 offset:21952
	ds_read_b32 v216, v87
	ds_read_b32 v217, v87 offset:4
	ds_read_b32 v218, v87 offset:8
	ds_read_b32 v219, v87 offset:12
	ds_read_b32 v101, v100
	ds_read_b32 v252, v100 offset:64
	s_waitcnt lgkmcnt(13)
	v_mfma_f32_16x16x32_bf16 v[36:39], v[182:185], v[186:189], v[36:39]
	s_waitcnt lgkmcnt(12)
	v_mfma_f32_16x16x32_bf16 v[32:35], v[182:185], v[220:223], v[32:35]
	s_waitcnt lgkmcnt(10)
	v_mfma_f32_16x16x32_bf16 v[36:39], v[224:227], v[228:231], v[36:39]
	s_waitcnt lgkmcnt(9)
	v_mfma_f32_16x16x32_bf16 v[32:35], v[224:227], v[232:235], v[32:35]
	s_waitcnt lgkmcnt(7)
	v_mfma_f32_16x16x32_bf16 v[36:39], v[236:239], v[240:243], v[36:39]
	s_waitcnt lgkmcnt(6)
	v_mfma_f32_16x16x32_bf16 v[32:35], v[236:239], v[244:247], v[32:35]
	s_waitcnt lgkmcnt(0)
	v_mov_b32_e32 v228, v252
	v_sub_f32_e32 v220, v216, v101
	v_sub_f32_e32 v221, v217, v101
	v_sub_f32_e32 v222, v218, v101
	v_sub_f32_e32 v223, v219, v101
	v_sub_f32_e32 v224, v216, v228
	v_sub_f32_e32 v225, v217, v228
	v_sub_f32_e32 v226, v218, v228
	v_sub_f32_e32 v227, v219, v228
	v_mul_f32_e32 v220, 0x3fb8aa3b, v220
	v_mul_f32_e32 v221, 0x3fb8aa3b, v221
	v_mul_f32_e32 v222, 0x3fb8aa3b, v222
	v_mul_f32_e32 v223, 0x3fb8aa3b, v223
	v_mul_f32_e32 v224, 0x3fb8aa3b, v224
	v_mul_f32_e32 v225, 0x3fb8aa3b, v225
	v_mul_f32_e32 v226, 0x3fb8aa3b, v226
	v_mul_f32_e32 v227, 0x3fb8aa3b, v227
	v_exp_f32_e32 v220, v220
	v_exp_f32_e32 v221, v221
	v_exp_f32_e32 v222, v222
	v_exp_f32_e32 v223, v223
	v_exp_f32_e32 v224, v224
	v_exp_f32_e32 v225, v225
	v_exp_f32_e32 v226, v226
	v_exp_f32_e32 v227, v227
	v_mul_f32_e32 v220, v36, v220
	v_mul_f32_e32 v221, v37, v221
	v_mul_f32_e32 v222, v38, v222
	v_mul_f32_e32 v223, v39, v223
	v_mul_f32_e32 v224, v32, v224
	v_mul_f32_e32 v225, v33, v225
	v_mul_f32_e32 v226, v34, v226
	v_mul_f32_e32 v227, v35, v227
	v_cvt_pk_bf16_f32 v220, v220, s0
	v_cvt_pk_bf16_f32 v221, v221, s0
	v_cvt_pk_bf16_f32 v222, v222, s0
	v_cvt_pk_bf16_f32 v223, v223, s0
	v_cvt_pk_bf16_f32 v224, v224, s0
	v_cvt_pk_bf16_f32 v225, v225, s0
	v_cvt_pk_bf16_f32 v226, v226, s0
	v_cvt_pk_bf16_f32 v227, v227, s0
	v_cndmask_b32_e64 v220, 0, v220, s[6:7]
	v_cndmask_b32_e64 v221, 0, v221, s[8:9]
	v_cndmask_b32_e64 v222, 0, v222, s[10:11]
	v_cndmask_b32_e64 v223, 0, v223, s[12:13]
	v_cndmask_b32_e64 v224, 0, v224, s[14:15]
	v_cndmask_b32_e64 v225, 0, v225, s[16:17]
	v_cndmask_b32_e64 v226, 0, v226, s[18:19]
	v_cndmask_b32_e64 v227, 0, v227, s[20:21]
	ds_write_b16 v124, v220
	ds_write_b16 v125, v221
	ds_write_b16 v126, v222
	ds_write_b16 v127, v223
	ds_write_b16 v128, v224
	ds_write_b16 v129, v225
	ds_write_b16 v130, v226
	v_mov_b32_e32 v32, v227
	v_mov_b32_e32 v33, s52
	ds_read_b32 v100, v33 offset:252
	ds_write_b16 v131, v32
	ds_read_b128 v[32:35], v134 offset:57856
	s_waitcnt lgkmcnt(7)
	ds_read_b128 v[36:39], v136 offset:34816
	ds_read_b128 v[178:181], v138 offset:34816
	ds_read_b128 v[182:185], v134 offset:57920
	ds_read_b128 v[186:189], v136 offset:34880
	s_waitcnt lgkmcnt(6)
	v_mul_f32_e32 v100, 0x3fb8aa3b, v100
	v_exp_f32_e32 v100, v100
	s_nop 0
	v_pk_mul_f32 v[6:7], v[6:7], v[100:101] op_sel_hi:[1,0]
	v_pk_mul_f32 v[4:5], v[4:5], v[100:101] op_sel_hi:[1,0]
	v_pk_mul_f32 v[2:3], v[2:3], v[100:101] op_sel_hi:[1,0]
	v_pk_mul_f32 v[0:1], v[0:1], v[100:101] op_sel_hi:[1,0]
	s_waitcnt lgkmcnt(3)
	v_mfma_f32_16x16x32_bf16 v[4:7], v[32:35], v[36:39], v[4:7]
	ds_read_b128 v[36:39], v138 offset:34880
	s_waitcnt lgkmcnt(3)
	v_mfma_f32_16x16x32_bf16 v[0:3], v[32:35], v[178:181], v[0:3]
	s_waitcnt lgkmcnt(1)
	v_mfma_f32_16x16x32_bf16 v[4:7], v[182:185], v[186:189], v[4:7]
	s_waitcnt lgkmcnt(0)
	v_mfma_f32_16x16x32_bf16 v[0:3], v[182:185], v[36:39], v[0:3]
	s_waitcnt lgkmcnt(0)
	s_barrier
; __device__ __forceinline__ float bf2f(u16 h) { return __uint_as_float(((unsigned)h) << 16); }
; __device__ __forceinline__ float siluf_(float v) { return v * __builtin_amdgcn_rcpf(1.f + __expf(-v)); }
; template <int DUMMY>
; __device__ void ssd_item(const Params& p, int item) {
;     ...
;     __builtin_amdgcn_s_setprio(1);
;     {
;       f32x4 yd = {0.f, 0.f, 0.f, 0.f}, yo = {0.f, 0.f, 0.f, 0.f};
; #pragma unroll
;       for (int ks = 0; ks < 2; ++ks) {
;         bf16x8 a = *(const bf16x8*)(Gs + (lf * 16 + fr) * 72 + ks * 32 + g4 * 8);
;         bf16x8 bb = *(const bf16x8*)(xdT + (pf * 16 + fr) * 72 + ks * 32 + g4 * 8);
;         yd = __builtin_amdgcn_mfma_f32_16x16x32_bf16(a, bb, yd, 0, 0, 0);
;       }
; #pragma unroll
;       for (int ks = 0; ks < 4; ++ks) {
;         bf16x8 a = *(const bf16x8*)(Cs + (lf * 16 + fr) * 136 + ks * 32 + g4 * 8);
;         bf16x8 bb = *(const bf16x8*)(Sb + (pf * 16 + fr) * 136 + ks * 32 + g4 * 8);
;         yo = __builtin_amdgcn_mfma_f32_16x16x32_bf16(a, bb, yo, 0, 0, 0);
;       }
;       __builtin_amdgcn_s_setprio(0);
;       bf16x4 xs4 = *(const bf16x4*)(xT + (pf * 16 + fr) * 72 + lf * 16 + g4 * 4);
; #pragma unroll
;       for (int r = 0; r < 4; ++r) {
;         int l_ = lf * 16 + g4 * 4 + r;
;         float y = yd[r] + __expf(cs[l_]) * yo[r] + Dh * bf2f((u16)xs4[r]);
;         y *= siluf_(bf2f(zcur[r]));
;         ytile[l_ * 36 + pf * 16 + fr] = f2bf(y);
;         float sq = row16_sum(y * y);
;         if (fr == 0) sqs[wid * 16 + g4 * 4 + r] = sq;
;       }
;       zbase += (size_t)64 * 4096;
;     }
;     cur3 = nxt3;
	ds_read_b128 v[32:35], v42
	v_add3_u32 v100, s78, v162, v161
	ds_read_b128 v[36:39], v100
	ds_read_b128 v[178:181], v132
	ds_read_b128 v[182:185], v42 offset:64
	ds_read_b128 v[186:189], v100 offset:64
	v_add3_u32 v101, s53, v160, v161
	s_waitcnt lgkmcnt(3)
	v_mfma_f32_16x16x32_bf16 v[32:35], v[32:35], v[36:39], 0
	ds_read_b128 v[36:39], v101
	ds_read_b128 v[190:193], v132 offset:64
	ds_read_b128 v[194:197], v101 offset:64
	s_waitcnt lgkmcnt(2)
	v_mfma_f32_16x16x32_bf16 v[178:181], v[178:181], v[36:39], 0
	ds_read_b128 v[36:39], v42 offset:128
	ds_read_b128 v[198:201], v42 offset:192
	v_mfma_f32_16x16x32_bf16 v[32:35], v[182:185], v[186:189], v[32:35]
	ds_read_b128 v[182:185], v100 offset:128
	ds_read_b128 v[186:189], v100 offset:192
	s_waitcnt lgkmcnt(1)
	v_mfma_f32_16x16x32_bf16 v[32:35], v[36:39], v[182:185], v[32:35]
	s_waitcnt lgkmcnt(0)
	v_mfma_f32_16x16x32_bf16 v[36:39], v[198:201], v[186:189], v[32:35]
	v_mfma_f32_16x16x32_bf16 v[32:35], v[190:193], v[194:197], v[178:181]
	v_add_u32_e32 v42, s77, v160
	v_add3_u32 v42, v42, v163, v164
	ds_read_b64 v[100:101], v42
	v_lshlrev_b32_e32 v220, 16, v167
	v_lshlrev_b32_e32 v221, 16, v166
	v_lshlrev_b32_e32 v222, 16, v165
	v_lshlrev_b32_e32 v223, 16, v75
	v_mul_f32_e32 v224, 0xbfb8aa3b, v220
	v_mul_f32_e32 v225, 0xbfb8aa3b, v221
	v_mul_f32_e32 v226, 0xbfb8aa3b, v222
	v_mul_f32_e32 v227, 0xbfb8aa3b, v223
	v_mul_f32_e32 v228, 0x3fb8aa3b, v216
	v_mul_f32_e32 v229, 0x3fb8aa3b, v217
	v_mul_f32_e32 v230, 0x3fb8aa3b, v218
	v_mul_f32_e32 v231, 0x3fb8aa3b, v219
	v_exp_f32_e32 v224, v224
	v_exp_f32_e32 v225, v225
	v_exp_f32_e32 v226, v226
	v_exp_f32_e32 v227, v227
	v_exp_f32_e32 v228, v228
	v_exp_f32_e32 v229, v229
	v_exp_f32_e32 v230, v230
	v_exp_f32_e32 v231, v231
	v_add_f32_e32 v224, 1.0, v224
	v_add_f32_e32 v225, 1.0, v225
	v_add_f32_e32 v226, 1.0, v226
	v_add_f32_e32 v227, 1.0, v227
	v_rcp_f32_e32 v224, v224
	v_rcp_f32_e32 v225, v225
	v_rcp_f32_e32 v226, v226
	v_rcp_f32_e32 v227, v227
	v_fma_f32 v32, v36, v228, v32
	v_fma_f32 v33, v37, v229, v33
	v_fma_f32 v34, v38, v230, v34
	v_fmac_f32_e32 v35, v39, v231
	s_waitcnt lgkmcnt(0)
	v_lshlrev_b32_e32 v232, 16, v100
	v_and_b32_e32 v233, 0xffff0000, v100
	v_lshlrev_b32_e32 v234, 16, v101
	v_and_b32_e32 v235, 0xffff0000, v101
	v_fmac_f32_e32 v32, v43, v232
	v_mul_f32_e32 v233, v43, v233
	v_mul_f32_e32 v234, v43, v234
	v_mul_f32_e32 v235, v43, v235
	v_add_f32_e32 v33, v233, v33
	v_add_f32_e32 v34, v234, v34
	v_add_f32_e32 v35, v235, v35
	v_mul_f32_e32 v224, v224, v220
	v_mul_f32_e32 v225, v225, v221
	v_mul_f32_e32 v226, v226, v222
	v_mul_f32_e32 v227, v227, v223
	v_mul_f32_e32 v32, v224, v32
	v_mul_f32_e32 v33, v225, v33
	v_mul_f32_e32 v34, v226, v34
	v_mul_f32_e32 v35, v227, v35
	v_cvt_pk_bf16_f32 v228, v32, s0
	v_cvt_pk_bf16_f32 v229, v33, s0
	v_cvt_pk_bf16_f32 v230, v34, s0
	v_cvt_pk_bf16_f32 v231, v35, s0
	ds_write_b16 v123, v228
	ds_write_b16 v123, v229 offset:72
	ds_write_b16 v123, v230 offset:144
	ds_write_b16 v123, v231 offset:216
	v_mul_f32_e32 v236, v32, v32
	v_mul_f32_e32 v237, v33, v33
	v_mul_f32_e32 v238, v34, v34
	v_mul_f32_e32 v239, v35, v35
	v_mov_b32_dpp v240, v236 quad_perm:[1,0,3,2] row_mask:0xf bank_mask:0xf bound_ctrl:1
	v_mov_b32_dpp v241, v237 quad_perm:[1,0,3,2] row_mask:0xf bank_mask:0xf bound_ctrl:1
	v_mov_b32_dpp v242, v238 quad_perm:[1,0,3,2] row_mask:0xf bank_mask:0xf bound_ctrl:1
	v_mov_b32_dpp v243, v239 quad_perm:[1,0,3,2] row_mask:0xf bank_mask:0xf bound_ctrl:1
	v_fmac_f32_e32 v240, v32, v32
	v_fmac_f32_e32 v241, v33, v33
	v_fmac_f32_e32 v242, v34, v34
	v_fmac_f32_e32 v243, v35, v35
	v_add_f32_dpp v236, v240, v240 quad_perm:[2,3,0,1] row_mask:0xf bank_mask:0xf bound_ctrl:1
	v_add_f32_dpp v237, v241, v241 quad_perm:[2,3,0,1] row_mask:0xf bank_mask:0xf bound_ctrl:1
	v_add_f32_dpp v238, v242, v242 quad_perm:[2,3,0,1] row_mask:0xf bank_mask:0xf bound_ctrl:1
	v_add_f32_dpp v239, v243, v243 quad_perm:[2,3,0,1] row_mask:0xf bank_mask:0xf bound_ctrl:1
	v_add_f32_dpp v236, v236, v236 row_half_mirror row_mask:0xf bank_mask:0xf bound_ctrl:1
	v_add_f32_dpp v237, v237, v237 row_half_mirror row_mask:0xf bank_mask:0xf bound_ctrl:1
	v_add_f32_dpp v238, v238, v238 row_half_mirror row_mask:0xf bank_mask:0xf bound_ctrl:1
	v_add_f32_dpp v239, v239, v239 row_half_mirror row_mask:0xf bank_mask:0xf bound_ctrl:1
	v_mov_b32_dpp v240, v236 row_mirror row_mask:0xf bank_mask:0xf bound_ctrl:1
	v_mov_b32_dpp v241, v237 row_mirror row_mask:0xf bank_mask:0xf bound_ctrl:1
	v_mov_b32_dpp v242, v238 row_mirror row_mask:0xf bank_mask:0xf bound_ctrl:1
	v_mov_b32_dpp v243, v239 row_mirror row_mask:0xf bank_mask:0xf bound_ctrl:1
	s_and_saveexec_b64 s[30:31], s[0:1]
	v_add_f32_e32 v236, v236, v240
	v_add_f32_e32 v237, v237, v241
	v_add_f32_e32 v238, v238, v242
	v_add_f32_e32 v239, v239, v243
	ds_write_b32 v122, v236
	ds_write_b32 v122, v237 offset:4
	ds_write_b32 v122, v238 offset:8
	ds_write_b32 v122, v239 offset:12
	s_or_b64 exec, exec, s[30:31]
	s_add_u32 s70, s70, 0x40000
	s_addc_u32 s71, s71, 0
	s_mov_b64 s[30:31], 0x4000
	s_add_i32 s76, s76, 1
	s_waitcnt vmcnt(4)
	v_perm_b32 v42, v40, v176, s94
	v_perm_b32 v100, v176, v175, s94
	v_perm_b32 v101, v175, v173, s94
	v_perm_b32 v173, v173, v174, s94
	v_perm_b32 v171, v172, v171, s94
	v_lshl_add_u64 v[84:85], v[84:85], 0, s[60:61]
	v_add_u32_e32 v86, 64, v86
	v_lshl_add_u64 v[92:93], v[92:93], 0, s[30:31]
	v_lshl_add_u64 v[94:95], v[94:95], 0, s[62:63]
	v_lshl_add_u64 v[96:97], v[96:97], 0, s[62:63]
	s_cmp_eq_u32 s70, 0x1f00000
	v_lshl_add_u64 v[98:99], v[98:99], 0, s[60:61]
	s_waitcnt vmcnt(0)
	v_mov_b32_e32 v118, v255
	s_cbranch_scc1 .LBB0_1077
; template <int DUMMY>
; __device__ void ssd_item(const Params& p, int item) {
;     ...
;     for (int r = 0; r < 4; ++r) zcur[r] = znext[r];
;     if (c > 1) {
;       const size_t yi = (tb + (c - 2) * 64 + (tid >> 3)) * 4096 + h * 64 + ph * 32 + (tid & 7) * 4;
;       *(i32x2*)(zyo + (yi & omask)) = ypend;
;     }
;     if (c + 1 < 128) {
;       load_raw(c + 1);
;       const size_t zn = zbase + (size_t)64 * 4096;
; #pragma unroll
;       for (int r = 0; r < 4; ++r) znext[r] = zy[zn + (size_t)r * 4096];
	s_waitcnt vmcnt(0)
	v_mov_b32_e32 v75, v49
	v_mov_b32_e32 v165, v168
	v_mov_b32_e32 v166, v169
	v_mov_b32_e32 v167, v170
	v_lshl_add_u64 v[224:225], v[78:79], 0, s[70:71]
	v_lshl_add_u64 v[226:227], v[80:81], 0, s[70:71]
	v_add_co_u32_e32 v224, vcc, 0x100000, v224
	s_nop 1
	v_addc_co_u32_e32 v225, vcc, 0, v225, vcc
	v_add_co_u32_e32 v226, vcc, 0x100000, v226
	s_nop 1
	v_addc_co_u32_e32 v227, vcc, 0, v227, vcc
	global_load_dword v228, v[224:225], off
	global_load_dword v228, v[224:225], off offset:2048
	global_load_dword v228, v[226:227], off
	global_load_dword v228, v[226:227], off offset:2048
	v_add_u32_e32 v224, 61, v86
	v_mov_b32_e32 v225, v41
	v_lshl_add_u64 v[224:225], s[64:65], 0, v[224:225]
	v_mad_u64_u32 v[226:227], s[72:73], v224, s86, v[66:67]
	v_mad_i32_i24 v227, v225, s86, v227
	global_load_ushort v228, v[226:227], off
	v_add_co_u32_e32 v226, vcc, 0x3000, v226
	s_nop 1
	v_addc_co_u32_e32 v227, vcc, 0, v227, vcc
	global_load_ushort v228, v[226:227], off
	v_add_co_u32_e32 v226, vcc, 0x3000, v226
	s_nop 1
	v_addc_co_u32_e32 v227, vcc, 0, v227, vcc
	global_load_ushort v228, v[226:227], off
	v_add_co_u32_e32 v226, vcc, 0x3000, v226
	s_nop 1
	v_addc_co_u32_e32 v227, vcc, 0, v227, vcc
	global_load_ushort v228, v[226:227], off
	v_lshl_add_u64 v[224:225], v[84:85], 0, s[60:61]
	v_lshl_add_u64 v[224:225], s[42:43], 0, v[224:225]
	v_add_co_u32_e32 v226, vcc, 0xb280000, v224
	s_nop 1
	v_addc_co_u32_e32 v227, vcc, 0, v225, vcc
	global_load_ushort v228, v[226:227], off
	v_add_co_u32_e32 v226, vcc, 0xb282000, v224
	s_nop 1
	v_addc_co_u32_e32 v227, vcc, 0, v225, vcc
	global_load_ushort v228, v[226:227], off
	v_add_co_u32_e32 v226, vcc, 0xb284000, v224
	s_nop 1
	v_addc_co_u32_e32 v227, vcc, 0, v225, vcc
	global_load_ushort v228, v[226:227], off
	v_add_co_u32_e32 v226, vcc, 0xb286000, v224
	s_nop 1
	v_addc_co_u32_e32 v227, vcc, 0, v225, vcc
	global_load_ushort v228, v[226:227], off
	s_branch .LBB0_1033
